# NSA phase: s_setprio toggles removed, one static priority raise for waves 0-3 (opposite half), on top of v21
# baseline (speedup 1.0000x reference)
; __device__ __forceinline__ void run_phase(const Params& P, int ph, char* lds) {
;     ...
;       nsa_tables(P, blockIdx.x & 1, lds);
;       for (int it = blockIdx.x; it < 1024; it += gridDim.x) {
;         const int rnd = it / 256, pos = it % 256;
;         const int c = (rnd & 1) ? (rnd >> 1) * 16 + (pos >> 4) : 63 - (rnd >> 1) * 16 - (pos >> 4);
;         const int bg = pos & 15;
;         nsa_item(P, bg >> 1, bg & 1, c, big, kcv, abuf, lds);
.LBB0_190:
	s_or_b64 exec, exec, s[0:1]
	v_readlane_b32 s0, v253, 1
	v_readlane_b32 s1, v253, 2
	s_andn2_b64 vcc, exec, s[0:1]
	s_waitcnt lgkmcnt(0)
	s_barrier
	s_cbranch_vccnz .LBB0_498
	v_readfirstlane_b32 s0, v179
	s_cmpk_lt_u32 s0, 0x100
	s_cbranch_scc0 .Lmy_prio
	s_setprio 1
